# grid-barrier seams: the acquire L1 invalidate is issued on arrival (next to the release write-back, as an acq_rel fence) instead of after the release, so it is hidden under the wait
# baseline (speedup 1.0000x reference)
; __device__ __forceinline__ unsigned xb_ld(unsigned* p)              { return __hip_atomic_load(p, __ATOMIC_RELAXED, __HIP_MEMORY_SCOPE_AGENT); }
; __device__ __forceinline__ unsigned xb_add(unsigned* p, unsigned v) { return __hip_atomic_fetch_add(p, v, __ATOMIC_RELAXED, __HIP_MEMORY_SCOPE_AGENT); }
; #define XB_SPIN(cond, bar) do { unsigned _sp = 0; while (cond) { __builtin_amdgcn_s_sleep(1); \
;     if ((++_sp & 255u) == 0u) { if (xb_ld(&(bar)[XB_TMO])) break; if (_sp > XB_SPIN_CAP) { atomicAdd(&(bar)[XB_TMO], 1u); break; } } } } while (0)
; __device__ __forceinline__ void xcd_barrier(const XcdBarrier& b) {
;     ...
;         const unsigned old = xb_add(&bar[XB_XSUB(b.x)], 1u);
;         const unsigned gen = old / nloc;
;         if (old + 1u == (gen + 1u) * nloc) {
;             __builtin_amdgcn_fence(__ATOMIC_RELEASE, "agent");
;             asm volatile("s_waitcnt vmcnt(0)" ::: "memory");
;             const unsigned og = xb_add(&bar[XB_TOP], 1u);
;             const unsigned tg = og / nx;
;             if (og + 1u == (tg + 1u) * nx) xb_add(&bar[XB_TOPGEN], 1u);
;             else XB_SPIN(xb_ld(&bar[XB_TOPGEN]) == tg, bar);
;             __builtin_amdgcn_fence(__ATOMIC_ACQUIRE, "agent");
;             xb_add(&bar[XB_XGEN(b.x)], 1u);
;             asm volatile("s_waitcnt vmcnt(0)" ::: "memory");
;         } else {
;             XB_SPIN(xb_ld(&bar[XB_XGEN(b.x)]) == gen, bar);
.LBB0_92:
	s_or_b64 exec, exec, s[12:13]
	v_cvt_f32_u32_e32 v6, v4
	s_waitcnt vmcnt(0)
	v_readfirstlane_b32 s0, v5
	v_sub_u32_e32 v5, 0, v4
	v_rcp_iflag_f32_e32 v6, v6
	v_add_u32_e32 v7, s0, v3
	v_mul_f32_e32 v6, 0x4f7ffffe, v6
	v_cvt_u32_f32_e32 v6, v6
	v_mul_lo_u32 v3, v5, v6
	v_mul_hi_u32 v3, v6, v3
	v_add_u32_e32 v3, v6, v3
	v_mul_hi_u32 v3, v7, v3
	v_mul_lo_u32 v5, v3, v4
	v_sub_u32_e32 v5, v7, v5
	v_add_u32_e32 v6, 1, v3
	v_cmp_ge_u32_e32 vcc, v5, v4
	s_nop 1
	v_cndmask_b32_e32 v3, v3, v6, vcc
	v_sub_u32_e32 v6, v5, v4
	v_cndmask_b32_e32 v5, v5, v6, vcc
	v_add_u32_e32 v6, 1, v3
	v_cmp_ge_u32_e32 vcc, v5, v4
	v_add_u32_e32 v5, 1, v7
	s_nop 0
	v_cndmask_b32_e32 v3, v3, v6, vcc
	v_mul_lo_u32 v6, v4, v3
	v_add_u32_e32 v4, v6, v4
	v_cmp_ne_u32_e32 vcc, v5, v4
	s_and_saveexec_b64 s[0:1], vcc
	s_xor_b64 s[10:11], exec, s[0:1]
	s_cbranch_execz .LBB0_106
	s_waitcnt lgkmcnt(0)
	v_mov_b32_e32 v2, 0x2000
	buffer_inv sc1
	global_load_dword v2, v2, s[8:9] offset:1024 sc1
	s_add_u32 s16, s8, 0x2400
	s_addc_u32 s17, s9, 0
	s_waitcnt vmcnt(0)
	v_cmp_eq_u32_e32 vcc, v2, v3
	s_and_saveexec_b64 s[12:13], vcc
	s_cbranch_execz .LBB0_105
	s_add_u32 s14, s30, 0xc0200
	s_addc_u32 s15, s31, 0
	s_mov_b32 s0, 1
	s_mov_b64 s[18:19], 0
	v_mov_b32_e32 v2, 0
	s_branch .LBB0_96

; __device__ __forceinline__ unsigned xb_ld(unsigned* p)              { return __hip_atomic_load(p, __ATOMIC_RELAXED, __HIP_MEMORY_SCOPE_AGENT); }
; __device__ __forceinline__ unsigned xb_add(unsigned* p, unsigned v) { return __hip_atomic_fetch_add(p, v, __ATOMIC_RELAXED, __HIP_MEMORY_SCOPE_AGENT); }
; #define XB_SPIN(cond, bar) do { unsigned _sp = 0; while (cond) { __builtin_amdgcn_s_sleep(1); \
;     if ((++_sp & 255u) == 0u) { if (xb_ld(&(bar)[XB_TMO])) break; if (_sp > XB_SPIN_CAP) { atomicAdd(&(bar)[XB_TMO], 1u); break; } } } } while (0)
; __device__ __forceinline__ void xcd_barrier(const XcdBarrier& b) {
;     ...
;         if (old + 1u == (gen + 1u) * nloc) {
;             __builtin_amdgcn_fence(__ATOMIC_RELEASE, "agent");
;             asm volatile("s_waitcnt vmcnt(0)" ::: "memory");
;             const unsigned og = xb_add(&bar[XB_TOP], 1u);
;             const unsigned tg = og / nx;
;             if (og + 1u == (tg + 1u) * nx) xb_add(&bar[XB_TOPGEN], 1u);
;             else XB_SPIN(xb_ld(&bar[XB_TOPGEN]) == tg, bar);
;             __builtin_amdgcn_fence(__ATOMIC_ACQUIRE, "agent");
;             xb_add(&bar[XB_XGEN(b.x)], 1u);
.LBB0_105:
	s_or_b64 exec, exec, s[12:13]
	s_waitcnt vmcnt(0)
	s_waitcnt vmcnt(0)
.LBB0_106:
	s_andn2_saveexec_b64 s[0:1], s[10:11]
	s_cbranch_execz .LBB0_126
	s_mov_b64 s[10:11], exec
	buffer_wbl2 sc1
	buffer_inv sc1
	s_waitcnt lgkmcnt(0)
	s_waitcnt vmcnt(0)
	v_mbcnt_lo_u32_b32 v3, s10, 0
	v_mbcnt_hi_u32_b32 v3, s11, v3
	v_cmp_eq_u32_e32 vcc, 0, v3
	s_and_saveexec_b64 s[12:13], vcc
	s_cbranch_execz .LBB0_109
	s_bcnt1_i32_b64 s0, s[10:11]
	v_mov_b32_e32 v4, 0xc3000
	v_mov_b32_e32 v5, s0
	global_atomic_add v4, v4, v5, s[30:31] offset:1024 sc0

; __device__ __forceinline__ unsigned xb_ld(unsigned* p)              { return __hip_atomic_load(p, __ATOMIC_RELAXED, __HIP_MEMORY_SCOPE_AGENT); }
; __device__ __forceinline__ unsigned xb_add(unsigned* p, unsigned v) { return __hip_atomic_fetch_add(p, v, __ATOMIC_RELAXED, __HIP_MEMORY_SCOPE_AGENT); }
; #define XB_SPIN(cond, bar) do { unsigned _sp = 0; while (cond) { __builtin_amdgcn_s_sleep(1); \
;     if ((++_sp & 255u) == 0u) { if (xb_ld(&(bar)[XB_TMO])) break; if (_sp > XB_SPIN_CAP) { atomicAdd(&(bar)[XB_TMO], 1u); break; } } } } while (0)
; __device__ __forceinline__ void xcd_barrier(const XcdBarrier& b) {
;     ...
;             const unsigned og = xb_add(&bar[XB_TOP], 1u);
;             const unsigned tg = og / nx;
;             if (og + 1u == (tg + 1u) * nx) xb_add(&bar[XB_TOPGEN], 1u);
;             else XB_SPIN(xb_ld(&bar[XB_TOPGEN]) == tg, bar);
;             __builtin_amdgcn_fence(__ATOMIC_ACQUIRE, "agent");
;             xb_add(&bar[XB_XGEN(b.x)], 1u);
.LBB0_123:
	s_or_b64 exec, exec, s[10:11]
	s_mov_b64 s[10:11], exec
	v_mbcnt_lo_u32_b32 v2, s10, 0
	v_mbcnt_hi_u32_b32 v2, s11, v2
	v_cmp_eq_u32_e32 vcc, 0, v2
	s_waitcnt vmcnt(0)
	s_and_saveexec_b64 s[12:13], vcc
	s_cbranch_execz .LBB0_125
	s_bcnt1_i32_b64 s0, s[10:11]
	v_mov_b32_e32 v2, 0x2000
	v_mov_b32_e32 v3, s0
	global_atomic_add v2, v3, s[8:9] offset:1024

; __device__ __forceinline__ unsigned xb_ld(unsigned* p)              { return __hip_atomic_load(p, __ATOMIC_RELAXED, __HIP_MEMORY_SCOPE_AGENT); }
; __device__ __forceinline__ unsigned xb_add(unsigned* p, unsigned v) { return __hip_atomic_fetch_add(p, v, __ATOMIC_RELAXED, __HIP_MEMORY_SCOPE_AGENT); }
; #define XB_SPIN(cond, bar) do { unsigned _sp = 0; while (cond) { __builtin_amdgcn_s_sleep(1); \
;     if ((++_sp & 255u) == 0u) { if (xb_ld(&(bar)[XB_TMO])) break; if (_sp > XB_SPIN_CAP) { atomicAdd(&(bar)[XB_TMO], 1u); break; } } } } while (0)
; __device__ __forceinline__ void xcd_barrier(const XcdBarrier& b) {
;     ...
;         const unsigned old = xb_add(&bar[XB_XSUB(b.x)], 1u);
;         const unsigned gen = old / nloc;
;         if (old + 1u == (gen + 1u) * nloc) {
;             __builtin_amdgcn_fence(__ATOMIC_RELEASE, "agent");
;             asm volatile("s_waitcnt vmcnt(0)" ::: "memory");
;             const unsigned og = xb_add(&bar[XB_TOP], 1u);
;             const unsigned tg = og / nx;
;             if (og + 1u == (tg + 1u) * nx) xb_add(&bar[XB_TOPGEN], 1u);
;             else XB_SPIN(xb_ld(&bar[XB_TOPGEN]) == tg, bar);
;             __builtin_amdgcn_fence(__ATOMIC_ACQUIRE, "agent");
;             xb_add(&bar[XB_XGEN(b.x)], 1u);
;             asm volatile("s_waitcnt vmcnt(0)" ::: "memory");
;         } else {
;             XB_SPIN(xb_ld(&bar[XB_XGEN(b.x)]) == gen, bar);
.LBB0_775:
	s_or_b64 exec, exec, s[8:9]
	v_cvt_f32_u32_e32 v6, v4
	s_waitcnt vmcnt(0)
	v_readfirstlane_b32 s6, v5
	v_sub_u32_e32 v5, 0, v4
	v_rcp_iflag_f32_e32 v6, v6
	v_add_u32_e32 v7, s6, v3
	v_mul_f32_e32 v6, 0x4f7ffffe, v6
	v_cvt_u32_f32_e32 v6, v6
	v_mul_lo_u32 v3, v5, v6
	v_mul_hi_u32 v3, v6, v3
	v_add_u32_e32 v3, v6, v3
	v_mul_hi_u32 v3, v7, v3
	v_mul_lo_u32 v5, v3, v4
	v_sub_u32_e32 v5, v7, v5
	v_add_u32_e32 v6, 1, v3
	v_cmp_ge_u32_e32 vcc, v5, v4
	s_nop 1
	v_cndmask_b32_e32 v3, v3, v6, vcc
	v_sub_u32_e32 v6, v5, v4
	v_cndmask_b32_e32 v5, v5, v6, vcc
	v_add_u32_e32 v6, 1, v3
	v_cmp_ge_u32_e32 vcc, v5, v4
	v_add_u32_e32 v5, 1, v7
	s_nop 0
	v_cndmask_b32_e32 v3, v3, v6, vcc
	v_mul_lo_u32 v6, v4, v3
	v_add_u32_e32 v4, v6, v4
	v_cmp_ne_u32_e32 vcc, v5, v4
	s_and_saveexec_b64 s[6:7], vcc
	s_xor_b64 s[6:7], exec, s[6:7]
	s_cbranch_execz .LBB0_789
	s_waitcnt lgkmcnt(0)
	v_mov_b32_e32 v2, 0x2000
	buffer_inv sc1
	global_load_dword v2, v2, s[0:1] offset:1024 sc1
	s_add_u32 s12, s0, 0x2400
	s_addc_u32 s13, s1, 0
	s_waitcnt vmcnt(0)
	v_cmp_eq_u32_e32 vcc, v2, v3
	s_and_saveexec_b64 s[8:9], vcc
	s_cbranch_execz .LBB0_788
	s_add_u32 s10, s30, 0xc0200
	s_addc_u32 s11, s31, 0
	s_mov_b32 s24, 1
	s_mov_b64 s[14:15], 0
	v_mov_b32_e32 v2, 0
	s_branch .LBB0_779

; __device__ __forceinline__ unsigned xb_ld(unsigned* p)              { return __hip_atomic_load(p, __ATOMIC_RELAXED, __HIP_MEMORY_SCOPE_AGENT); }
; __device__ __forceinline__ unsigned xb_add(unsigned* p, unsigned v) { return __hip_atomic_fetch_add(p, v, __ATOMIC_RELAXED, __HIP_MEMORY_SCOPE_AGENT); }
; #define XB_SPIN(cond, bar) do { unsigned _sp = 0; while (cond) { __builtin_amdgcn_s_sleep(1); \
;     if ((++_sp & 255u) == 0u) { if (xb_ld(&(bar)[XB_TMO])) break; if (_sp > XB_SPIN_CAP) { atomicAdd(&(bar)[XB_TMO], 1u); break; } } } } while (0)
; __device__ __forceinline__ void xcd_barrier(const XcdBarrier& b) {
;     ...
;         if (old + 1u == (gen + 1u) * nloc) {
;             __builtin_amdgcn_fence(__ATOMIC_RELEASE, "agent");
;             asm volatile("s_waitcnt vmcnt(0)" ::: "memory");
;             const unsigned og = xb_add(&bar[XB_TOP], 1u);
;             const unsigned tg = og / nx;
;             if (og + 1u == (tg + 1u) * nx) xb_add(&bar[XB_TOPGEN], 1u);
;             else XB_SPIN(xb_ld(&bar[XB_TOPGEN]) == tg, bar);
;             __builtin_amdgcn_fence(__ATOMIC_ACQUIRE, "agent");
;             xb_add(&bar[XB_XGEN(b.x)], 1u);
.LBB0_788:
	s_or_b64 exec, exec, s[8:9]
	s_waitcnt vmcnt(0)
	s_waitcnt vmcnt(0)
.LBB0_789:
	s_andn2_saveexec_b64 s[6:7], s[6:7]
	s_cbranch_execz .LBB0_809
	s_mov_b64 s[6:7], exec
	buffer_wbl2 sc1
	buffer_inv sc1
	s_waitcnt lgkmcnt(0)
	s_waitcnt vmcnt(0)
	v_mbcnt_lo_u32_b32 v3, s6, 0
	v_mbcnt_hi_u32_b32 v3, s7, v3
	v_cmp_eq_u32_e32 vcc, 0, v3
	s_and_saveexec_b64 s[8:9], vcc
	s_cbranch_execz .LBB0_792
	s_bcnt1_i32_b64 s6, s[6:7]
	v_mov_b32_e32 v4, 0xc3000
	v_mov_b32_e32 v5, s6
	global_atomic_add v4, v4, v5, s[30:31] offset:1024 sc0

; __device__ __forceinline__ unsigned xb_ld(unsigned* p)              { return __hip_atomic_load(p, __ATOMIC_RELAXED, __HIP_MEMORY_SCOPE_AGENT); }
; __device__ __forceinline__ unsigned xb_add(unsigned* p, unsigned v) { return __hip_atomic_fetch_add(p, v, __ATOMIC_RELAXED, __HIP_MEMORY_SCOPE_AGENT); }
; #define XB_SPIN(cond, bar) do { unsigned _sp = 0; while (cond) { __builtin_amdgcn_s_sleep(1); \
;     if ((++_sp & 255u) == 0u) { if (xb_ld(&(bar)[XB_TMO])) break; if (_sp > XB_SPIN_CAP) { atomicAdd(&(bar)[XB_TMO], 1u); break; } } } } while (0)
; __device__ __forceinline__ void xcd_barrier(const XcdBarrier& b) {
;     ...
;             const unsigned og = xb_add(&bar[XB_TOP], 1u);
;             const unsigned tg = og / nx;
;             if (og + 1u == (tg + 1u) * nx) xb_add(&bar[XB_TOPGEN], 1u);
;             else XB_SPIN(xb_ld(&bar[XB_TOPGEN]) == tg, bar);
;             __builtin_amdgcn_fence(__ATOMIC_ACQUIRE, "agent");
;             xb_add(&bar[XB_XGEN(b.x)], 1u);
.LBB0_806:
	s_or_b64 exec, exec, s[6:7]
	s_mov_b64 s[6:7], exec
	v_mbcnt_lo_u32_b32 v2, s6, 0
	v_mbcnt_hi_u32_b32 v2, s7, v2
	v_cmp_eq_u32_e32 vcc, 0, v2
	s_waitcnt vmcnt(0)
	s_and_saveexec_b64 s[8:9], vcc
	s_cbranch_execz .LBB0_808
	s_bcnt1_i32_b64 s6, s[6:7]
	v_mov_b32_e32 v2, 0x2000
	v_mov_b32_e32 v3, s6
	global_atomic_add v2, v3, s[0:1] offset:1024
